# v19 + w_in GEMM walks its rounds in reverse (gate columns first, Q/K/V columns last) so the attention phase finds its freshly written inputs in the Infinity Cache
# baseline (speedup 1.0000x reference)
.LBB0_215:
	s_mov_b32 s6, s33
	s_cmp_lg_u32 s96, 0x100
	s_cbranch_scc1 .Lp2norev0
	s_addk_i32 s6, 0x1600
.Lp2norev0:
	s_ashr_i32 s3, s6, 31
	s_lshr_b32 s3, s3, 29
	s_add_i32 s3, s6, s3
	s_ashr_i32 s4, s3, 3
	s_and_b32 s3, s3, -8
	s_sub_i32 s3, s6, s3
	s_cmp_lt_i32 s3, 0
	s_movk_i32 s5, 0x2e1
	s_cselect_b32 s5, s5, 0x2e0
	s_mul_i32 s3, s3, s5
	s_add_i32 s3, s3, s4
	s_mul_hi_i32 s4, s3, 0xb21642c9
	s_add_i32 s4, s4, s3
	s_lshr_b32 s5, s4, 31
	s_ashr_i32 s4, s4, 9
	s_add_i32 s4, s4, s5
	s_lshl_b32 s5, s4, 3
	s_mulk_i32 s4, 0x2e0
	s_sub_i32 s3, s3, s4
	s_sext_i32_i16 s4, s3
	s_bfe_u32 s4, s4, 0x3001c
	s_add_i32 s4, s3, s4
	s_sext_i32_i16 s6, s4
	s_and_b32 s4, s4, 0xfff8
	s_sub_i32 s3, s3, s4
	s_sext_i32_i16 s3, s3
	s_add_i32 s4, s5, s3
	s_ashr_i32 s6, s6, 3
	s_andn2_b64 vcc, exec, s[0:1]
	s_cbranch_vccnz .LBB0_214

.LBB0_221:
	s_add_i32 s43, s43, 1
	s_sub_i32 vcc_lo, 22, s43
	s_cmp_eq_u32 s96, 0x100
	s_cselect_b32 vcc_lo, vcc_lo, s43
	s_mul_i32 s2, vcc_lo, s74
	s_mul_hi_u32 s3, vcc_lo, s96
	s_add_i32 s3, s3, s2
	s_mul_i32 s2, vcc_lo, s96
	s_add_u32 s24, s2, s33
	s_addc_u32 s25, s3, s75
	v_cmp_gt_i64_e32 vcc, s[24:25], v[162:163]
	v_cmp_lt_i64_e64 s[2:3], s[24:25], v[160:161]
	s_cbranch_vccnz .LBB0_223
	s_ashr_i32 s5, s24, 31
	s_lshr_b32 s5, s5, 29
	s_add_i32 s5, s24, s5
	s_ashr_i32 s7, s5, 3
	s_and_b32 s5, s5, -8
	s_sub_i32 s5, s24, s5
	s_cmp_lt_i32 s5, 0
	s_movk_i32 s20, 0x2e1
	s_cselect_b32 s20, s20, 0x2e0
	s_mul_i32 s5, s5, s20
	s_add_i32 s5, s5, s7
	s_mul_hi_i32 s7, s5, 0xb21642c9
	s_add_i32 s7, s7, s5
	s_lshr_b32 s20, s7, 31
	s_ashr_i32 s7, s7, 9
	s_add_i32 s7, s7, s20
	s_lshl_b32 s21, s7, 3
	s_sub_i32 s20, 64, s21
	s_min_i32 s22, s20, 8
	s_abs_i32 s20, s22
	v_cvt_f32_u32_e32 v1, s20
	s_sub_i32 s24, 0, s20
	s_mulk_i32 s7, 0x2e0
	s_sub_i32 s5, s5, s7
	v_rcp_iflag_f32_e32 v1, v1
	s_abs_i32 s7, s5
	s_xor_b32 s23, s5, s22
	s_ashr_i32 s23, s23, 31
	v_mul_f32_e32 v1, 0x4f7ffffe, v1
	v_cvt_u32_f32_e32 v1, v1
	s_nop 0
	v_readfirstlane_b32 s25, v1
	s_mul_i32 s24, s24, s25
	s_mul_hi_u32 s24, s25, s24
	s_add_i32 s25, s25, s24
	s_mul_hi_u32 s24, s7, s25
	s_mul_i32 s25, s24, s20
	s_sub_i32 s7, s7, s25
	s_add_i32 s26, s24, 1
	s_sub_i32 s25, s7, s20
	s_cmp_ge_u32 s7, s20
	s_cselect_b32 s24, s26, s24
	s_cselect_b32 s7, s25, s7
	s_add_i32 s25, s24, 1
	s_cmp_ge_u32 s7, s20
	s_cselect_b32 s7, s25, s24
	s_xor_b32 s7, s7, s23
	s_sub_i32 s20, s7, s23
	s_mul_i32 s7, s20, s22
	s_sub_i32 s5, s5, s7
	s_add_i32 s22, s21, s5
